# nt cache hint on GEMM1 epilogue stores
# speedup vs baseline: 1.0028x; 1.0028x over previous
; __device__ __forceinline__ unsigned cvt_pk_bf16(float lo, float hi) { f32x2_t v = {lo, hi}; bf16x2_t b = __builtin_convertvector(v, bf16x2_t); return __builtin_bit_cast(unsigned, b); }
; #define EPI_FENCE() asm volatile("" ::: "memory")
; #define EPI_LANE() int t__ = threadIdx.x; asm volatile("" : "+v"(t__)); const int wid__ = __builtin_amdgcn_readfirstlane(t__ >> 6); wr = wid__ >> 2; wc = wid__ & 3; fr = t__ & 15; fq = (t__ & 63) >> 4
;     template <int MODE> __device__ __forceinline__ void run(const f32x4 (&acc)[2][2][4][2], const Unit& u, int wr, int wc, int fr, int fq) const {
;         EPI_LANE();
;         const int pn = u.pn, colt = pn * BM, t = colt >> 9;
;         char* base = (MODE == 2) ? (char*)(O + (size_t)6 * ((size_t)MTOK * 512)) + ((size_t)(((pn - 12) * 128 + u.pm) * 8 + wid__)) * 16384
;                                  : (char*)(O + (size_t)t * ((size_t)MTOK * 512) + (size_t)u.pm * BM * 512 + (colt & 511));
;         unsigned off0 = (MODE == 2) ? (unsigned)((t__ & 63) * 16) : (unsigned)((wr * 64 + fr) * 512 + wc * 32 + 8 * fq) * 2u; asm volatile("" : "+v"(off0));
; #pragma unroll
;         for (int bj = 0; bj < 2; ++bj) {
; #pragma unroll
;             for (int ai = 0; ai < 2; ++ai)
; #pragma unroll
;                 for (int m = 0; m < 4; ++m) { const unsigned off = off0 + ((MODE == 2) ? (unsigned)(((ai * 4 + m) * 2 + bj) * 1024) : (unsigned)((ai * HALF + m * 16) * 512 + bj * HALF) * 2u);
;                     const f32x4 v0 = acc[ai][bj][m][0], v1 = acc[ai][bj][m][1];
;                     u32x4 w; w.x = cvt_pk_bf16(actf<MODE>(v0[0]), actf<MODE>(v0[1])); w.y = cvt_pk_bf16(actf<MODE>(v0[2]), actf<MODE>(v0[3]));
;                     w.z = cvt_pk_bf16(actf<MODE>(v1[0]), actf<MODE>(v1[1])); w.w = cvt_pk_bf16(actf<MODE>(v1[2]), actf<MODE>(v1[3]));
;                     *(u32x4*)(base + off) = w; }
;             EPI_FENCE();
;         }
;     }
.LBB0_403:
	v_mul_f32_e32 v12, 0xbfb8aa3b, v12
	v_mul_f32_e32 v13, 0xbfb8aa3b, v13
	v_exp_f32_e32 v12, v12
	v_exp_f32_e32 v13, v13
	v_mul_f32_e32 v14, 0xbfb8aa3b, v14
	v_mul_f32_e32 v15, 0xbfb8aa3b, v15
	v_mul_f32_e32 v8, 0xbfb8aa3b, v8
	v_mul_f32_e32 v9, 0xbfb8aa3b, v9
	v_exp_f32_e32 v14, v14
	v_exp_f32_e32 v15, v15
	v_exp_f32_e32 v8, v8
	v_exp_f32_e32 v9, v9
	v_mul_f32_e32 v10, 0xbfb8aa3b, v10
	v_mul_f32_e32 v11, 0xbfb8aa3b, v11
	v_add_f32_e32 v12, 1.0, v12
	v_add_f32_e32 v13, 1.0, v13
	v_exp_f32_e32 v10, v10
	v_exp_f32_e32 v11, v11
	v_mul_f32_e32 v76, 0xbfb8aa3b, v76
	v_mul_f32_e32 v77, 0xbfb8aa3b, v77
	v_min_f32_e32 v12, 0x7149f2ca, v12
	v_min_f32_e32 v13, 0x7149f2ca, v13
	v_exp_f32_e32 v76, v76
	v_exp_f32_e32 v77, v77
	v_cvt_pk_bf16_f32 v12, v12, v13
	v_add_f32_e32 v13, 1.0, v14
	v_add_f32_e32 v14, 1.0, v15
	v_add_f32_e32 v8, 1.0, v8
	v_add_f32_e32 v9, 1.0, v9
	v_mul_f32_e32 v78, 0xbfb8aa3b, v78
	v_mul_f32_e32 v79, 0xbfb8aa3b, v79
	v_mul_f32_e32 v72, 0xbfb8aa3b, v72
	v_mul_f32_e32 v73, 0xbfb8aa3b, v73
	v_min_f32_e32 v13, 0x7149f2ca, v13
	v_min_f32_e32 v14, 0x7149f2ca, v14
	v_min_f32_e32 v8, 0x7149f2ca, v8
	v_min_f32_e32 v9, 0x7149f2ca, v9
	v_mov_b32_e32 v142, v212
	s_lshl_b32 s60, s72, 7
	v_exp_f32_e32 v78, v78
	v_exp_f32_e32 v79, v79
	v_exp_f32_e32 v72, v72
	v_exp_f32_e32 v73, v73
	v_cvt_pk_bf16_f32 v13, v13, v14
	v_cvt_pk_bf16_f32 v14, v8, v9
	v_add_f32_e32 v8, 1.0, v10
	v_add_f32_e32 v9, 1.0, v11
	s_add_i32 s60, s60, s54
	v_readfirstlane_b32 s55, v142
	v_mul_f32_e32 v74, 0xbfb8aa3b, v74
	v_mul_f32_e32 v75, 0xbfb8aa3b, v75
	v_min_f32_e32 v8, 0x7149f2ca, v8
	v_min_f32_e32 v9, 0x7149f2ca, v9
	s_ashr_i32 s55, s55, 6
	s_lshl_b32 s54, s60, 3
	v_add_f32_e32 v76, 1.0, v76
	v_add_f32_e32 v77, 1.0, v77
	v_exp_f32_e32 v74, v74
	v_exp_f32_e32 v75, v75
	v_cvt_pk_bf16_f32 v15, v8, v9
	v_mul_f32_e32 v8, 0xbfb8aa3b, v68
	v_mul_f32_e32 v9, 0xbfb8aa3b, v69
	s_add_i32 s54, s54, s55
	v_min_f32_e32 v76, 0x7149f2ca, v76
	v_min_f32_e32 v77, 0x7149f2ca, v77
	v_exp_f32_e32 v8, v8
	v_exp_f32_e32 v9, v9
	s_addk_i32 s54, 0xd000
	v_cvt_pk_bf16_f32 v76, v76, v77
	v_add_f32_e32 v77, 1.0, v78
	v_add_f32_e32 v78, 1.0, v79
	v_add_f32_e32 v72, 1.0, v72
	v_add_f32_e32 v73, 1.0, v73
	v_mul_f32_e32 v10, 0xbfb8aa3b, v70
	v_mul_f32_e32 v11, 0xbfb8aa3b, v71
	s_ashr_i32 s55, s54, 31
	v_min_f32_e32 v77, 0x7149f2ca, v77
	v_min_f32_e32 v78, 0x7149f2ca, v78
	v_min_f32_e32 v72, 0x7149f2ca, v72
	v_min_f32_e32 v73, 0x7149f2ca, v73
	v_exp_f32_e32 v10, v10
	v_exp_f32_e32 v11, v11
	s_lshl_b64 s[54:55], s[54:55], 14
	v_lshlrev_b32_e32 v142, 4, v142
	v_cvt_pk_bf16_f32 v77, v77, v78
	v_cvt_pk_bf16_f32 v78, v72, v73
	v_add_f32_e32 v72, 1.0, v74
	v_add_f32_e32 v73, 1.0, v75
	s_add_u32 s54, s33, s54
	v_and_b32_e32 v142, 0x3f0, v142
	v_min_f32_e32 v72, 0x7149f2ca, v72
	v_min_f32_e32 v73, 0x7149f2ca, v73
	v_add_f32_e32 v8, 1.0, v8
	v_add_f32_e32 v9, 1.0, v9
	s_addc_u32 s55, s37, s55
	v_cvt_pk_bf16_f32 v79, v72, v73
	v_add_u32_e32 v72, 0x3800, v142
	v_min_f32_e32 v8, 0x7149f2ca, v8
	v_min_f32_e32 v9, 0x7149f2ca, v9
	v_mul_f32_e32 v126, 0xbfb8aa3b, v126
	v_mul_f32_e32 v127, 0xbfb8aa3b, v127
	v_mul_f32_e32 v118, 0xbfb8aa3b, v118
	v_mul_f32_e32 v119, 0xbfb8aa3b, v119
	v_mul_f32_e32 v110, 0xbfb8aa3b, v110
	v_mul_f32_e32 v111, 0xbfb8aa3b, v111
	v_mul_f32_e32 v102, 0xbfb8aa3b, v102
	v_mul_f32_e32 v103, 0xbfb8aa3b, v103
	v_mul_f32_e32 v92, 0xbfb8aa3b, v92
	v_mul_f32_e32 v93, 0xbfb8aa3b, v93
	v_mul_f32_e32 v84, 0xbfb8aa3b, v84
	v_mul_f32_e32 v85, 0xbfb8aa3b, v85
	global_store_dwordx4 v72, v[12:15], s[54:55] nt
	v_cvt_pk_bf16_f32 v8, v8, v9
	v_add_f32_e32 v9, 1.0, v10
	v_add_f32_e32 v10, 1.0, v11
	v_mul_f32_e32 v11, 0xbfb8aa3b, v64
	v_mul_f32_e32 v13, 0xbfb8aa3b, v65
	v_exp_f32_e32 v126, v126
	v_exp_f32_e32 v127, v127
	v_exp_f32_e32 v118, v118
	v_exp_f32_e32 v119, v119
	v_exp_f32_e32 v110, v110
	v_exp_f32_e32 v111, v111
	v_exp_f32_e32 v102, v102
	v_exp_f32_e32 v103, v103
	v_exp_f32_e32 v92, v92
	v_exp_f32_e32 v93, v93
	v_exp_f32_e32 v84, v84
	v_exp_f32_e32 v85, v85
	v_exp_f32_e32 v11, v11
	v_exp_f32_e32 v13, v13
	v_mul_f32_e32 v128, 0xbfb8aa3b, v128
	v_mul_f32_e32 v129, 0xbfb8aa3b, v129
	v_mul_f32_e32 v122, 0xbfb8aa3b, v122
	v_mul_f32_e32 v123, 0xbfb8aa3b, v123
	v_mul_f32_e32 v120, 0xbfb8aa3b, v120
	v_mul_f32_e32 v121, 0xbfb8aa3b, v121
	v_mul_f32_e32 v114, 0xbfb8aa3b, v114
	v_mul_f32_e32 v115, 0xbfb8aa3b, v115
	v_mul_f32_e32 v112, 0xbfb8aa3b, v112
	v_mul_f32_e32 v113, 0xbfb8aa3b, v113
	v_mul_f32_e32 v106, 0xbfb8aa3b, v106
	v_mul_f32_e32 v107, 0xbfb8aa3b, v107
	v_mul_f32_e32 v104, 0xbfb8aa3b, v104
	v_mul_f32_e32 v105, 0xbfb8aa3b, v105
	v_mul_f32_e32 v98, 0xbfb8aa3b, v98
	v_mul_f32_e32 v99, 0xbfb8aa3b, v99
	v_mul_f32_e32 v94, 0xbfb8aa3b, v94
	v_mul_f32_e32 v95, 0xbfb8aa3b, v95
	v_mul_f32_e32 v88, 0xbfb8aa3b, v88
	v_mul_f32_e32 v89, 0xbfb8aa3b, v89
	v_mul_f32_e32 v86, 0xbfb8aa3b, v86
	v_mul_f32_e32 v87, 0xbfb8aa3b, v87
	v_mul_f32_e32 v80, 0xbfb8aa3b, v80
	v_mul_f32_e32 v81, 0xbfb8aa3b, v81
	v_exp_f32_e32 v128, v128
	v_exp_f32_e32 v129, v129
	v_exp_f32_e32 v122, v122
	v_exp_f32_e32 v123, v123
	v_exp_f32_e32 v120, v120
	v_exp_f32_e32 v121, v121
	v_exp_f32_e32 v114, v114
	v_exp_f32_e32 v115, v115
	v_exp_f32_e32 v112, v112
	v_exp_f32_e32 v113, v113
	v_exp_f32_e32 v106, v106
	v_exp_f32_e32 v107, v107
	v_exp_f32_e32 v104, v104
	v_exp_f32_e32 v105, v105
	v_exp_f32_e32 v98, v98
	v_exp_f32_e32 v99, v99
	v_exp_f32_e32 v94, v94
	v_exp_f32_e32 v95, v95
	v_exp_f32_e32 v88, v88
	v_exp_f32_e32 v89, v89
	v_exp_f32_e32 v86, v86
	v_exp_f32_e32 v87, v87
	v_exp_f32_e32 v80, v80
	v_exp_f32_e32 v81, v81
	v_mul_f32_e32 v124, 0xbfb8aa3b, v124
	v_mul_f32_e32 v125, 0xbfb8aa3b, v125
	v_mul_f32_e32 v116, 0xbfb8aa3b, v116
; __device__ __forceinline__ unsigned cvt_pk_bf16(float lo, float hi) { f32x2_t v = {lo, hi}; bf16x2_t b = __builtin_convertvector(v, bf16x2_t); return __builtin_bit_cast(unsigned, b); }
; #define EPI_FENCE() asm volatile("" ::: "memory")
; #define EPI_LANE() int t__ = threadIdx.x; asm volatile("" : "+v"(t__)); const int wid__ = __builtin_amdgcn_readfirstlane(t__ >> 6); wr = wid__ >> 2; wc = wid__ & 3; fr = t__ & 15; fq = (t__ & 63) >> 4
;     template <int MODE> __device__ __forceinline__ void run(const f32x4 (&acc)[2][2][4][2], const Unit& u, int wr, int wc, int fr, int fq) const {
;         EPI_LANE();
;         const int pn = u.pn, colt = pn * BM, t = colt >> 9;
;         char* base = (MODE == 2) ? (char*)(O + (size_t)6 * ((size_t)MTOK * 512)) + ((size_t)(((pn - 12) * 128 + u.pm) * 8 + wid__)) * 16384
;                                  : (char*)(O + (size_t)t * ((size_t)MTOK * 512) + (size_t)u.pm * BM * 512 + (colt & 511));
;         unsigned off0 = (MODE == 2) ? (unsigned)((t__ & 63) * 16) : (unsigned)((wr * 64 + fr) * 512 + wc * 32 + 8 * fq) * 2u; asm volatile("" : "+v"(off0));
; #pragma unroll
;         for (int bj = 0; bj < 2; ++bj) {
; #pragma unroll
;             for (int ai = 0; ai < 2; ++ai)
; #pragma unroll
;                 for (int m = 0; m < 4; ++m) { const unsigned off = off0 + ((MODE == 2) ? (unsigned)(((ai * 4 + m) * 2 + bj) * 1024) : (unsigned)((ai * HALF + m * 16) * 512 + bj * HALF) * 2u);
;                     const f32x4 v0 = acc[ai][bj][m][0], v1 = acc[ai][bj][m][1];
;                     u32x4 w; w.x = cvt_pk_bf16(actf<MODE>(v0[0]), actf<MODE>(v0[1])); w.y = cvt_pk_bf16(actf<MODE>(v0[2]), actf<MODE>(v0[3]));
;                     w.z = cvt_pk_bf16(actf<MODE>(v1[0]), actf<MODE>(v1[1])); w.w = cvt_pk_bf16(actf<MODE>(v1[2]), actf<MODE>(v1[3]));
;                     *(u32x4*)(base + off) = w; }
;             EPI_FENCE();
;         }
;     }
	v_mul_f32_e32 v117, 0xbfb8aa3b, v117
	v_mul_f32_e32 v108, 0xbfb8aa3b, v108
	v_mul_f32_e32 v109, 0xbfb8aa3b, v109
	v_mul_f32_e32 v100, 0xbfb8aa3b, v100
	v_mul_f32_e32 v101, 0xbfb8aa3b, v101
	v_mul_f32_e32 v90, 0xbfb8aa3b, v90
	v_mul_f32_e32 v91, 0xbfb8aa3b, v91
	v_mul_f32_e32 v82, 0xbfb8aa3b, v82
	v_mul_f32_e32 v83, 0xbfb8aa3b, v83
	v_min_f32_e32 v9, 0x7149f2ca, v9
	v_min_f32_e32 v10, 0x7149f2ca, v10
	v_add_f32_e32 v126, 1.0, v126
	v_add_f32_e32 v127, 1.0, v127
	v_exp_f32_e32 v124, v124
	v_exp_f32_e32 v125, v125
	v_add_f32_e32 v118, 1.0, v118
	v_add_f32_e32 v119, 1.0, v119
	v_exp_f32_e32 v116, v116
	v_exp_f32_e32 v117, v117
	v_add_f32_e32 v110, 1.0, v110
	v_add_f32_e32 v111, 1.0, v111
	v_exp_f32_e32 v108, v108
	v_exp_f32_e32 v109, v109
	v_add_f32_e32 v102, 1.0, v102
	v_add_f32_e32 v103, 1.0, v103
	v_exp_f32_e32 v100, v100
	v_exp_f32_e32 v101, v101
	v_add_f32_e32 v92, 1.0, v92
	v_add_f32_e32 v93, 1.0, v93
	v_exp_f32_e32 v90, v90
	v_exp_f32_e32 v91, v91
	v_add_f32_e32 v84, 1.0, v84
	v_add_f32_e32 v85, 1.0, v85
	v_exp_f32_e32 v82, v82
	v_exp_f32_e32 v83, v83
	v_cvt_pk_bf16_f32 v9, v9, v10
	v_add_f32_e32 v10, 1.0, v11
	v_add_f32_e32 v11, 1.0, v13
	v_mul_f32_e32 v13, 0xbfb8aa3b, v66
	v_mul_f32_e32 v14, 0xbfb8aa3b, v67
	v_min_f32_e32 v126, 0x7149f2ca, v126
	v_min_f32_e32 v127, 0x7149f2ca, v127
	v_min_f32_e32 v118, 0x7149f2ca, v118
	v_min_f32_e32 v119, 0x7149f2ca, v119
	v_min_f32_e32 v110, 0x7149f2ca, v110
	v_min_f32_e32 v111, 0x7149f2ca, v111
	v_min_f32_e32 v102, 0x7149f2ca, v102
	v_min_f32_e32 v103, 0x7149f2ca, v103
	v_min_f32_e32 v92, 0x7149f2ca, v92
	v_min_f32_e32 v93, 0x7149f2ca, v93
	v_min_f32_e32 v84, 0x7149f2ca, v84
	v_min_f32_e32 v85, 0x7149f2ca, v85
	v_exp_f32_e32 v13, v13
	v_exp_f32_e32 v14, v14
	v_cvt_pk_bf16_f32 v126, v126, v127
	v_add_f32_e32 v127, 1.0, v128
	v_add_f32_e32 v128, 1.0, v129
	v_add_f32_e32 v122, 1.0, v122
	v_add_f32_e32 v123, 1.0, v123
	v_cvt_pk_bf16_f32 v118, v118, v119
	v_add_f32_e32 v119, 1.0, v120
	v_add_f32_e32 v120, 1.0, v121
	v_add_f32_e32 v114, 1.0, v114
	v_add_f32_e32 v115, 1.0, v115
	v_cvt_pk_bf16_f32 v110, v110, v111
	v_add_f32_e32 v111, 1.0, v112
	v_add_f32_e32 v112, 1.0, v113
	v_add_f32_e32 v106, 1.0, v106
	v_add_f32_e32 v107, 1.0, v107
	v_cvt_pk_bf16_f32 v102, v102, v103
	v_add_f32_e32 v103, 1.0, v104
	v_add_f32_e32 v104, 1.0, v105
	v_add_f32_e32 v98, 1.0, v98
	v_add_f32_e32 v99, 1.0, v99
	v_cvt_pk_bf16_f32 v92, v92, v93
	v_add_f32_e32 v93, 1.0, v94
	v_add_f32_e32 v94, 1.0, v95
	v_add_f32_e32 v88, 1.0, v88
	v_add_f32_e32 v89, 1.0, v89
	v_cvt_pk_bf16_f32 v84, v84, v85
	v_add_f32_e32 v85, 1.0, v86
	v_add_f32_e32 v86, 1.0, v87
	v_add_f32_e32 v80, 1.0, v80
	v_add_f32_e32 v81, 1.0, v81
	v_min_f32_e32 v127, 0x7149f2ca, v127
	v_min_f32_e32 v128, 0x7149f2ca, v128
	v_min_f32_e32 v122, 0x7149f2ca, v122
	v_min_f32_e32 v123, 0x7149f2ca, v123
	v_min_f32_e32 v119, 0x7149f2ca, v119
	v_min_f32_e32 v120, 0x7149f2ca, v120
	v_min_f32_e32 v114, 0x7149f2ca, v114
	v_min_f32_e32 v115, 0x7149f2ca, v115
	v_min_f32_e32 v111, 0x7149f2ca, v111
	v_min_f32_e32 v112, 0x7149f2ca, v112
	v_min_f32_e32 v106, 0x7149f2ca, v106
	v_min_f32_e32 v107, 0x7149f2ca, v107
	v_min_f32_e32 v103, 0x7149f2ca, v103
	v_min_f32_e32 v104, 0x7149f2ca, v104
	v_min_f32_e32 v98, 0x7149f2ca, v98
	v_min_f32_e32 v99, 0x7149f2ca, v99
	v_min_f32_e32 v93, 0x7149f2ca, v93
	v_min_f32_e32 v94, 0x7149f2ca, v94
	v_min_f32_e32 v88, 0x7149f2ca, v88
	v_min_f32_e32 v89, 0x7149f2ca, v89
	v_min_f32_e32 v85, 0x7149f2ca, v85
	v_min_f32_e32 v86, 0x7149f2ca, v86
	v_min_f32_e32 v80, 0x7149f2ca, v80
	v_min_f32_e32 v81, 0x7149f2ca, v81
	v_cvt_pk_bf16_f32 v127, v127, v128
	v_cvt_pk_bf16_f32 v128, v122, v123
	v_add_f32_e32 v122, 1.0, v124
	v_add_f32_e32 v123, 1.0, v125
	v_cvt_pk_bf16_f32 v119, v119, v120
	v_cvt_pk_bf16_f32 v120, v114, v115
	v_add_f32_e32 v114, 1.0, v116
	v_add_f32_e32 v115, 1.0, v117
	v_cvt_pk_bf16_f32 v111, v111, v112
	v_cvt_pk_bf16_f32 v112, v106, v107
	v_add_f32_e32 v106, 1.0, v108
	v_add_f32_e32 v107, 1.0, v109
	v_cvt_pk_bf16_f32 v103, v103, v104
	v_cvt_pk_bf16_f32 v104, v98, v99
	v_add_f32_e32 v98, 1.0, v100
	v_add_f32_e32 v99, 1.0, v101
	v_cvt_pk_bf16_f32 v93, v93, v94
	v_cvt_pk_bf16_f32 v94, v88, v89
	v_add_f32_e32 v88, 1.0, v90
	v_add_f32_e32 v89, 1.0, v91
	v_cvt_pk_bf16_f32 v85, v85, v86
	v_cvt_pk_bf16_f32 v86, v80, v81
	v_add_f32_e32 v80, 1.0, v82
	v_add_f32_e32 v81, 1.0, v83
	v_min_f32_e32 v10, 0x7149f2ca, v10
	v_min_f32_e32 v11, 0x7149f2ca, v11
	v_min_f32_e32 v122, 0x7149f2ca, v122
	v_min_f32_e32 v123, 0x7149f2ca, v123
	v_min_f32_e32 v114, 0x7149f2ca, v114
	v_min_f32_e32 v115, 0x7149f2ca, v115
	v_min_f32_e32 v106, 0x7149f2ca, v106
	v_min_f32_e32 v107, 0x7149f2ca, v107
	v_min_f32_e32 v98, 0x7149f2ca, v98
	v_min_f32_e32 v99, 0x7149f2ca, v99
	v_min_f32_e32 v88, 0x7149f2ca, v88
	v_min_f32_e32 v89, 0x7149f2ca, v89
	v_min_f32_e32 v80, 0x7149f2ca, v80
	v_min_f32_e32 v81, 0x7149f2ca, v81
	v_cvt_pk_bf16_f32 v10, v10, v11
	v_add_f32_e32 v11, 1.0, v13
	v_add_f32_e32 v13, 1.0, v14
	v_cvt_pk_bf16_f32 v129, v122, v123
	v_add_u32_e32 v122, 0x800, v142
	v_cvt_pk_bf16_f32 v121, v114, v115
	v_add_u32_e32 v114, 0x1000, v142
	v_cvt_pk_bf16_f32 v113, v106, v107
	v_add_u32_e32 v106, 0x1800, v142
	v_cvt_pk_bf16_f32 v105, v98, v99
	v_add_u32_e32 v98, 0x2000, v142
	v_cvt_pk_bf16_f32 v95, v88, v89
	v_add_u32_e32 v88, 0x2800, v142
	v_cvt_pk_bf16_f32 v87, v80, v81
	v_add_u32_e32 v80, 0x3000, v142
	v_min_f32_e32 v11, 0x7149f2ca, v11
	v_min_f32_e32 v13, 0x7149f2ca, v13
	global_store_dwordx4 v142, v[126:129], s[54:55] nt
	global_store_dwordx4 v122, v[118:121], s[54:55] nt
	global_store_dwordx4 v114, v[110:113], s[54:55] nt
	global_store_dwordx4 v106, v[102:105], s[54:55] nt
; __device__ __forceinline__ unsigned cvt_pk_bf16(float lo, float hi) { f32x2_t v = {lo, hi}; bf16x2_t b = __builtin_convertvector(v, bf16x2_t); return __builtin_bit_cast(unsigned, b); }
; #define EPI_FENCE() asm volatile("" ::: "memory")
; #define EPI_LANE() int t__ = threadIdx.x; asm volatile("" : "+v"(t__)); const int wid__ = __builtin_amdgcn_readfirstlane(t__ >> 6); wr = wid__ >> 2; wc = wid__ & 3; fr = t__ & 15; fq = (t__ & 63) >> 4
;     template <int MODE> __device__ __forceinline__ void run(const f32x4 (&acc)[2][2][4][2], const Unit& u, int wr, int wc, int fr, int fq) const {
;         EPI_LANE();
;         const int pn = u.pn, colt = pn * BM, t = colt >> 9;
;         char* base = (MODE == 2) ? (char*)(O + (size_t)6 * ((size_t)MTOK * 512)) + ((size_t)(((pn - 12) * 128 + u.pm) * 8 + wid__)) * 16384
;                                  : (char*)(O + (size_t)t * ((size_t)MTOK * 512) + (size_t)u.pm * BM * 512 + (colt & 511));
;         unsigned off0 = (MODE == 2) ? (unsigned)((t__ & 63) * 16) : (unsigned)((wr * 64 + fr) * 512 + wc * 32 + 8 * fq) * 2u; asm volatile("" : "+v"(off0));
; #pragma unroll
;         for (int bj = 0; bj < 2; ++bj) {
; #pragma unroll
;             for (int ai = 0; ai < 2; ++ai)
; #pragma unroll
;                 for (int m = 0; m < 4; ++m) { const unsigned off = off0 + ((MODE == 2) ? (unsigned)(((ai * 4 + m) * 2 + bj) * 1024) : (unsigned)((ai * HALF + m * 16) * 512 + bj * HALF) * 2u);
;                     const f32x4 v0 = acc[ai][bj][m][0], v1 = acc[ai][bj][m][1];
;                     u32x4 w; w.x = cvt_pk_bf16(actf<MODE>(v0[0]), actf<MODE>(v0[1])); w.y = cvt_pk_bf16(actf<MODE>(v0[2]), actf<MODE>(v0[3]));
;                     w.z = cvt_pk_bf16(actf<MODE>(v1[0]), actf<MODE>(v1[1])); w.w = cvt_pk_bf16(actf<MODE>(v1[2]), actf<MODE>(v1[3]));
;                     *(u32x4*)(base + off) = w; }
;             EPI_FENCE();
;         }
;     }
	global_store_dwordx4 v98, v[92:95], s[54:55] nt
	global_store_dwordx4 v88, v[84:87], s[54:55] nt
	global_store_dwordx4 v80, v[76:79], s[54:55] nt
	v_add_u32_e32 v12, 0x400, v142
	v_cvt_pk_bf16_f32 v11, v11, v13
	global_store_dwordx4 v12, v[8:11], s[54:55] nt
	v_mul_f32_e32 v13, 0xbfb8aa3b, v57
	v_exp_f32_e32 v13, v13
	v_mul_f32_e32 v8, 0xbfb8aa3b, v60
	v_mul_f32_e32 v9, 0xbfb8aa3b, v61
	v_exp_f32_e32 v8, v8
	v_exp_f32_e32 v9, v9
	v_mul_f32_e32 v10, 0xbfb8aa3b, v62
	v_mul_f32_e32 v11, 0xbfb8aa3b, v63
	v_exp_f32_e32 v10, v10
	v_exp_f32_e32 v11, v11
	v_add_f32_e32 v8, 1.0, v8
	v_add_f32_e32 v9, 1.0, v9
	v_min_f32_e32 v8, 0x7149f2ca, v8
	v_min_f32_e32 v9, 0x7149f2ca, v9
	v_cvt_pk_bf16_f32 v8, v8, v9
	v_add_f32_e32 v9, 1.0, v10
	v_add_f32_e32 v10, 1.0, v11
	v_mul_f32_e32 v11, 0xbfb8aa3b, v56
	v_exp_f32_e32 v11, v11
	v_min_f32_e32 v9, 0x7149f2ca, v9
	v_min_f32_e32 v10, 0x7149f2ca, v10
	v_cvt_pk_bf16_f32 v9, v9, v10
	v_add_f32_e32 v10, 1.0, v11
	v_add_f32_e32 v11, 1.0, v13
	v_mul_f32_e32 v13, 0xbfb8aa3b, v58
	v_mul_f32_e32 v14, 0xbfb8aa3b, v59
	v_exp_f32_e32 v13, v13
	v_exp_f32_e32 v14, v14
	v_min_f32_e32 v10, 0x7149f2ca, v10
	v_min_f32_e32 v11, 0x7149f2ca, v11
	v_cvt_pk_bf16_f32 v10, v10, v11
	v_add_f32_e32 v11, 1.0, v13
	v_add_f32_e32 v13, 1.0, v14
	v_min_f32_e32 v11, 0x7149f2ca, v11
	v_min_f32_e32 v13, 0x7149f2ca, v13
	v_add_u32_e32 v12, 0xc00, v142
	v_cvt_pk_bf16_f32 v11, v11, v13
	global_store_dwordx4 v12, v[8:11], s[54:55] nt
	v_mul_f32_e32 v13, 0xbfb8aa3b, v49
	v_exp_f32_e32 v13, v13
	v_mul_f32_e32 v8, 0xbfb8aa3b, v52
	v_mul_f32_e32 v9, 0xbfb8aa3b, v53
	v_exp_f32_e32 v8, v8
	v_exp_f32_e32 v9, v9
	v_mul_f32_e32 v10, 0xbfb8aa3b, v54
	v_mul_f32_e32 v11, 0xbfb8aa3b, v55
	v_exp_f32_e32 v10, v10
	v_exp_f32_e32 v11, v11
	v_add_f32_e32 v8, 1.0, v8
	v_add_f32_e32 v9, 1.0, v9
	v_min_f32_e32 v8, 0x7149f2ca, v8
	v_min_f32_e32 v9, 0x7149f2ca, v9
	v_cvt_pk_bf16_f32 v8, v8, v9
	v_add_f32_e32 v9, 1.0, v10
	v_add_f32_e32 v10, 1.0, v11
	v_mul_f32_e32 v11, 0xbfb8aa3b, v48
	v_exp_f32_e32 v11, v11
	v_min_f32_e32 v9, 0x7149f2ca, v9
	v_min_f32_e32 v10, 0x7149f2ca, v10
	v_cvt_pk_bf16_f32 v9, v9, v10
	v_add_f32_e32 v10, 1.0, v11
	v_add_f32_e32 v11, 1.0, v13
	v_mul_f32_e32 v13, 0xbfb8aa3b, v50
	v_mul_f32_e32 v14, 0xbfb8aa3b, v51
	v_exp_f32_e32 v13, v13
	v_exp_f32_e32 v14, v14
	v_min_f32_e32 v10, 0x7149f2ca, v10
	v_min_f32_e32 v11, 0x7149f2ca, v11
	v_cvt_pk_bf16_f32 v10, v10, v11
	v_add_f32_e32 v11, 1.0, v13
	v_add_f32_e32 v13, 1.0, v14
	v_min_f32_e32 v11, 0x7149f2ca, v11
	v_min_f32_e32 v13, 0x7149f2ca, v13
	v_add_u32_e32 v12, 0x1400, v142
	v_cvt_pk_bf16_f32 v11, v11, v13
	global_store_dwordx4 v12, v[8:11], s[54:55] nt
	v_mul_f32_e32 v13, 0xbfb8aa3b, v41
	v_exp_f32_e32 v13, v13
	v_mul_f32_e32 v8, 0xbfb8aa3b, v44
	v_mul_f32_e32 v9, 0xbfb8aa3b, v45
	v_exp_f32_e32 v8, v8
	v_exp_f32_e32 v9, v9
	v_mul_f32_e32 v10, 0xbfb8aa3b, v46
	v_mul_f32_e32 v11, 0xbfb8aa3b, v47
	v_exp_f32_e32 v10, v10
	v_exp_f32_e32 v11, v11
	v_add_f32_e32 v8, 1.0, v8
	v_add_f32_e32 v9, 1.0, v9
	v_min_f32_e32 v8, 0x7149f2ca, v8
	v_min_f32_e32 v9, 0x7149f2ca, v9
	v_cvt_pk_bf16_f32 v8, v8, v9
	v_add_f32_e32 v9, 1.0, v10
	v_add_f32_e32 v10, 1.0, v11
	v_mul_f32_e32 v11, 0xbfb8aa3b, v40
	v_exp_f32_e32 v11, v11
	v_min_f32_e32 v9, 0x7149f2ca, v9
	v_min_f32_e32 v10, 0x7149f2ca, v10
	v_cvt_pk_bf16_f32 v9, v9, v10
	v_add_f32_e32 v10, 1.0, v11
	v_add_f32_e32 v11, 1.0, v13
	v_mul_f32_e32 v13, 0xbfb8aa3b, v42
	v_mul_f32_e32 v14, 0xbfb8aa3b, v43
	v_exp_f32_e32 v13, v13
	v_exp_f32_e32 v14, v14
	v_min_f32_e32 v10, 0x7149f2ca, v10
	v_min_f32_e32 v11, 0x7149f2ca, v11
	v_cvt_pk_bf16_f32 v10, v10, v11
	v_add_f32_e32 v11, 1.0, v13
	v_add_f32_e32 v13, 1.0, v14
	v_min_f32_e32 v11, 0x7149f2ca, v11
	v_min_f32_e32 v13, 0x7149f2ca, v13
	v_add_u32_e32 v12, 0x1c00, v142
	v_cvt_pk_bf16_f32 v11, v11, v13
	global_store_dwordx4 v12, v[8:11], s[54:55] nt
	v_mul_f32_e32 v13, 0xbfb8aa3b, v33
	v_exp_f32_e32 v13, v13
	v_mul_f32_e32 v8, 0xbfb8aa3b, v36
	v_mul_f32_e32 v9, 0xbfb8aa3b, v37
	v_exp_f32_e32 v8, v8
	v_exp_f32_e32 v9, v9
	v_mul_f32_e32 v10, 0xbfb8aa3b, v38
	v_mul_f32_e32 v11, 0xbfb8aa3b, v39
	v_exp_f32_e32 v10, v10
	v_exp_f32_e32 v11, v11
	v_add_f32_e32 v8, 1.0, v8
	v_add_f32_e32 v9, 1.0, v9
	v_min_f32_e32 v8, 0x7149f2ca, v8
	v_min_f32_e32 v9, 0x7149f2ca, v9
	v_cvt_pk_bf16_f32 v8, v8, v9
; __device__ __forceinline__ unsigned cvt_pk_bf16(float lo, float hi) { f32x2_t v = {lo, hi}; bf16x2_t b = __builtin_convertvector(v, bf16x2_t); return __builtin_bit_cast(unsigned, b); }
; #define EPI_FENCE() asm volatile("" ::: "memory")
; #define EPI_LANE() int t__ = threadIdx.x; asm volatile("" : "+v"(t__)); const int wid__ = __builtin_amdgcn_readfirstlane(t__ >> 6); wr = wid__ >> 2; wc = wid__ & 3; fr = t__ & 15; fq = (t__ & 63) >> 4
;     template <int MODE> __device__ __forceinline__ void run(const f32x4 (&acc)[2][2][4][2], const Unit& u, int wr, int wc, int fr, int fq) const {
;         EPI_LANE();
;         const int pn = u.pn, colt = pn * BM, t = colt >> 9;
;         char* base = (MODE == 2) ? (char*)(O + (size_t)6 * ((size_t)MTOK * 512)) + ((size_t)(((pn - 12) * 128 + u.pm) * 8 + wid__)) * 16384
;                                  : (char*)(O + (size_t)t * ((size_t)MTOK * 512) + (size_t)u.pm * BM * 512 + (colt & 511));
;         unsigned off0 = (MODE == 2) ? (unsigned)((t__ & 63) * 16) : (unsigned)((wr * 64 + fr) * 512 + wc * 32 + 8 * fq) * 2u; asm volatile("" : "+v"(off0));
; #pragma unroll
;         for (int bj = 0; bj < 2; ++bj) {
; #pragma unroll
;             for (int ai = 0; ai < 2; ++ai)
; #pragma unroll
;                 for (int m = 0; m < 4; ++m) { const unsigned off = off0 + ((MODE == 2) ? (unsigned)(((ai * 4 + m) * 2 + bj) * 1024) : (unsigned)((ai * HALF + m * 16) * 512 + bj * HALF) * 2u);
;                     const f32x4 v0 = acc[ai][bj][m][0], v1 = acc[ai][bj][m][1];
;                     u32x4 w; w.x = cvt_pk_bf16(actf<MODE>(v0[0]), actf<MODE>(v0[1])); w.y = cvt_pk_bf16(actf<MODE>(v0[2]), actf<MODE>(v0[3]));
;                     w.z = cvt_pk_bf16(actf<MODE>(v1[0]), actf<MODE>(v1[1])); w.w = cvt_pk_bf16(actf<MODE>(v1[2]), actf<MODE>(v1[3]));
;                     *(u32x4*)(base + off) = w; }
;             EPI_FENCE();
;         }
;     }
	v_add_f32_e32 v9, 1.0, v10
	v_add_f32_e32 v10, 1.0, v11
	v_mul_f32_e32 v11, 0xbfb8aa3b, v32
	v_exp_f32_e32 v11, v11
	v_min_f32_e32 v9, 0x7149f2ca, v9
	v_min_f32_e32 v10, 0x7149f2ca, v10
	v_cvt_pk_bf16_f32 v9, v9, v10
	v_add_f32_e32 v10, 1.0, v11
	v_add_f32_e32 v11, 1.0, v13
	v_mul_f32_e32 v13, 0xbfb8aa3b, v34
	v_mul_f32_e32 v14, 0xbfb8aa3b, v35
	v_exp_f32_e32 v13, v13
	v_exp_f32_e32 v14, v14
	v_min_f32_e32 v10, 0x7149f2ca, v10
	v_min_f32_e32 v11, 0x7149f2ca, v11
	v_cvt_pk_bf16_f32 v10, v10, v11
	v_add_f32_e32 v11, 1.0, v13
	v_add_f32_e32 v13, 1.0, v14
	v_min_f32_e32 v11, 0x7149f2ca, v11
	v_min_f32_e32 v13, 0x7149f2ca, v13
	v_add_u32_e32 v12, 0x2400, v142
	v_cvt_pk_bf16_f32 v11, v11, v13
	global_store_dwordx4 v12, v[8:11], s[54:55] nt
	v_mul_f32_e32 v13, 0xbfb8aa3b, v25
	v_exp_f32_e32 v13, v13
	v_mul_f32_e32 v8, 0xbfb8aa3b, v28
	v_mul_f32_e32 v9, 0xbfb8aa3b, v29
	v_exp_f32_e32 v8, v8
	v_exp_f32_e32 v9, v9
	v_mul_f32_e32 v10, 0xbfb8aa3b, v30
	v_mul_f32_e32 v11, 0xbfb8aa3b, v31
	v_exp_f32_e32 v10, v10
	v_exp_f32_e32 v11, v11
	v_add_f32_e32 v8, 1.0, v8
	v_add_f32_e32 v9, 1.0, v9
	v_min_f32_e32 v8, 0x7149f2ca, v8
	v_min_f32_e32 v9, 0x7149f2ca, v9
	v_cvt_pk_bf16_f32 v8, v8, v9
	v_add_f32_e32 v9, 1.0, v10
	v_add_f32_e32 v10, 1.0, v11
	v_mul_f32_e32 v11, 0xbfb8aa3b, v24
	v_exp_f32_e32 v11, v11
	v_min_f32_e32 v9, 0x7149f2ca, v9
	v_min_f32_e32 v10, 0x7149f2ca, v10
	v_cvt_pk_bf16_f32 v9, v9, v10
	v_add_f32_e32 v10, 1.0, v11
	v_add_f32_e32 v11, 1.0, v13
	v_mul_f32_e32 v13, 0xbfb8aa3b, v26
	v_mul_f32_e32 v14, 0xbfb8aa3b, v27
	v_exp_f32_e32 v13, v13
	v_exp_f32_e32 v14, v14
	v_min_f32_e32 v10, 0x7149f2ca, v10
	v_min_f32_e32 v11, 0x7149f2ca, v11
	v_cvt_pk_bf16_f32 v10, v10, v11
	v_add_f32_e32 v11, 1.0, v13
	v_add_f32_e32 v13, 1.0, v14
	v_min_f32_e32 v11, 0x7149f2ca, v11
	v_min_f32_e32 v13, 0x7149f2ca, v13
	v_add_u32_e32 v12, 0x2c00, v142
	v_cvt_pk_bf16_f32 v11, v11, v13
	global_store_dwordx4 v12, v[8:11], s[54:55] nt
	v_mul_f32_e32 v13, 0xbfb8aa3b, v17
	v_exp_f32_e32 v13, v13
	v_mul_f32_e32 v8, 0xbfb8aa3b, v20
	v_mul_f32_e32 v9, 0xbfb8aa3b, v21
	v_exp_f32_e32 v8, v8
	v_exp_f32_e32 v9, v9
	v_mul_f32_e32 v10, 0xbfb8aa3b, v22
	v_mul_f32_e32 v11, 0xbfb8aa3b, v23
	v_exp_f32_e32 v10, v10
	v_exp_f32_e32 v11, v11
	v_add_f32_e32 v8, 1.0, v8
	v_add_f32_e32 v9, 1.0, v9
	v_min_f32_e32 v8, 0x7149f2ca, v8
	v_min_f32_e32 v9, 0x7149f2ca, v9
	v_cvt_pk_bf16_f32 v8, v8, v9
	v_add_f32_e32 v9, 1.0, v10
	v_add_f32_e32 v10, 1.0, v11
	v_mul_f32_e32 v11, 0xbfb8aa3b, v16
	v_exp_f32_e32 v11, v11
	v_mul_f32_e32 v4, 0xbfb8aa3b, v4
	v_mul_f32_e32 v5, 0xbfb8aa3b, v5
	v_exp_f32_e32 v4, v4
	v_exp_f32_e32 v5, v5
	v_min_f32_e32 v9, 0x7149f2ca, v9
	v_min_f32_e32 v10, 0x7149f2ca, v10
	v_mul_f32_e32 v6, 0xbfb8aa3b, v6
	v_mul_f32_e32 v7, 0xbfb8aa3b, v7
	v_mul_f32_e32 v0, 0xbfb8aa3b, v0
	v_mul_f32_e32 v1, 0xbfb8aa3b, v1
	v_cvt_pk_bf16_f32 v9, v9, v10
	v_add_f32_e32 v10, 1.0, v11
	v_add_f32_e32 v11, 1.0, v13
	v_mul_f32_e32 v13, 0xbfb8aa3b, v18
	v_mul_f32_e32 v14, 0xbfb8aa3b, v19
	v_exp_f32_e32 v6, v6
	v_exp_f32_e32 v7, v7
	v_exp_f32_e32 v0, v0
	v_exp_f32_e32 v1, v1
	v_exp_f32_e32 v13, v13
	v_exp_f32_e32 v14, v14
	v_mul_f32_e32 v2, 0xbfb8aa3b, v2
	v_mul_f32_e32 v3, 0xbfb8aa3b, v3
	v_add_f32_e32 v4, 1.0, v4
	v_add_f32_e32 v5, 1.0, v5
	v_exp_f32_e32 v2, v2
	v_exp_f32_e32 v3, v3
	v_min_f32_e32 v4, 0x7149f2ca, v4
	v_min_f32_e32 v5, 0x7149f2ca, v5
	v_min_f32_e32 v10, 0x7149f2ca, v10
	v_min_f32_e32 v11, 0x7149f2ca, v11
	v_cvt_pk_bf16_f32 v4, v4, v5
	v_add_f32_e32 v5, 1.0, v6
	v_add_f32_e32 v6, 1.0, v7
	v_add_f32_e32 v0, 1.0, v0
	v_add_f32_e32 v1, 1.0, v1
	v_cvt_pk_bf16_f32 v10, v10, v11
	v_add_f32_e32 v11, 1.0, v13
	v_add_f32_e32 v13, 1.0, v14
	v_min_f32_e32 v5, 0x7149f2ca, v5
	v_min_f32_e32 v6, 0x7149f2ca, v6
	v_min_f32_e32 v0, 0x7149f2ca, v0
	v_min_f32_e32 v1, 0x7149f2ca, v1
	v_min_f32_e32 v11, 0x7149f2ca, v11
	v_min_f32_e32 v13, 0x7149f2ca, v13
	v_cvt_pk_bf16_f32 v5, v5, v6
	v_cvt_pk_bf16_f32 v6, v0, v1
	v_add_f32_e32 v0, 1.0, v2
	v_add_f32_e32 v1, 1.0, v3
	v_add_u32_e32 v12, 0x3400, v142
	v_cvt_pk_bf16_f32 v11, v11, v13
	v_min_f32_e32 v0, 0x7149f2ca, v0
	v_min_f32_e32 v1, 0x7149f2ca, v1
	global_store_dwordx4 v12, v[8:11], s[54:55] nt
	v_cvt_pk_bf16_f32 v7, v0, v1
	s_nop 0
	v_add_u32_e32 v8, 0x3c00, v142
	global_store_dwordx4 v8, v[4:7], s[54:55] nt

; __device__ __forceinline__ unsigned cvt_pk_bf16(float lo, float hi) { f32x2_t v = {lo, hi}; bf16x2_t b = __builtin_convertvector(v, bf16x2_t); return __builtin_bit_cast(unsigned, b); }
; #define EPI_FENCE() asm volatile("" ::: "memory")
; #define EPI_LANE() int t__ = threadIdx.x; asm volatile("" : "+v"(t__)); const int wid__ = __builtin_amdgcn_readfirstlane(t__ >> 6); wr = wid__ >> 2; wc = wid__ & 3; fr = t__ & 15; fq = (t__ & 63) >> 4
;     template <int MODE> __device__ __forceinline__ void run(const f32x4 (&acc)[2][2][4][2], const Unit& u, int wr, int wc, int fr, int fq) const {
;         EPI_LANE();
;         const int pn = u.pn, colt = pn * BM, t = colt >> 9;
;         char* base = (MODE == 2) ? (char*)(O + (size_t)6 * ((size_t)MTOK * 512)) + ((size_t)(((pn - 12) * 128 + u.pm) * 8 + wid__)) * 16384
;                                  : (char*)(O + (size_t)t * ((size_t)MTOK * 512) + (size_t)u.pm * BM * 512 + (colt & 511));
;         unsigned off0 = (MODE == 2) ? (unsigned)((t__ & 63) * 16) : (unsigned)((wr * 64 + fr) * 512 + wc * 32 + 8 * fq) * 2u; asm volatile("" : "+v"(off0));
; #pragma unroll
;         for (int bj = 0; bj < 2; ++bj) {
; #pragma unroll
;             for (int ai = 0; ai < 2; ++ai)
; #pragma unroll
;                 for (int m = 0; m < 4; ++m) { const unsigned off = off0 + ((MODE == 2) ? (unsigned)(((ai * 4 + m) * 2 + bj) * 1024) : (unsigned)((ai * HALF + m * 16) * 512 + bj * HALF) * 2u);
;                     const f32x4 v0 = acc[ai][bj][m][0], v1 = acc[ai][bj][m][1];
;                     u32x4 w; w.x = cvt_pk_bf16(actf<MODE>(v0[0]), actf<MODE>(v0[1])); w.y = cvt_pk_bf16(actf<MODE>(v0[2]), actf<MODE>(v0[3]));
;                     w.z = cvt_pk_bf16(actf<MODE>(v1[0]), actf<MODE>(v1[1])); w.w = cvt_pk_bf16(actf<MODE>(v1[2]), actf<MODE>(v1[3]));
;                     *(u32x4*)(base + off) = w; }
;             EPI_FENCE();
;         }
;     }
.LBB0_411:
	s_and_b32 s55, s72, -2
	s_lshl_b32 s62, s72, 8
	s_cmp_lg_u32 s55, 2
	s_cbranch_scc0 .LBB0_413
	s_ashr_i32 s60, s72, 1
	s_ashr_i32 s61, s60, 31
	s_lshl_b64 s[60:61], s[60:61], 25
	s_add_u32 s73, s90, s60
	s_addc_u32 s74, s91, s61
	s_ashr_i32 s55, s54, 31
	s_lshl_b64 s[60:61], s[54:55], 18
	s_add_u32 s55, s73, s60
	s_addc_u32 s61, s74, s61
	s_and_b32 s60, s62, 0x100
	v_mov_b32_e32 v142, v212
	s_lshl_b32 s60, s60, 1
	s_add_u32 s60, s55, s60
	v_readfirstlane_b32 s63, v142
	s_addc_u32 s61, s61, 0
	s_lshr_b32 s55, s63, 2
	s_and_b32 s55, s55, 0x3fffc0
	v_and_or_b32 v143, v142, 15, s55
	v_lshlrev_b32_e32 v143, 10, v143
	s_and_b32 s55, s63, 0xc0
	v_and_b32_e32 v142, 48, v142
	v_or3_b32 v146, v143, s55, v142
	v_cvt_pk_bf16_f32 v142, v126, v127
	v_cvt_pk_bf16_f32 v143, v128, v129
	v_cvt_pk_bf16_f32 v144, v122, v123
	v_cvt_pk_bf16_f32 v145, v124, v125
	global_store_dwordx4 v146, v[142:145], s[60:61] nt
	v_add_u32_e32 v147, 0x4000, v146
	s_nop 0
	v_cvt_pk_bf16_f32 v142, v118, v119
	v_cvt_pk_bf16_f32 v143, v120, v121
	v_cvt_pk_bf16_f32 v144, v114, v115
	v_cvt_pk_bf16_f32 v145, v116, v117
	global_store_dwordx4 v147, v[142:145], s[60:61] nt
	v_add_u32_e32 v147, 0x8000, v146
	s_nop 0
	v_cvt_pk_bf16_f32 v142, v110, v111
	v_cvt_pk_bf16_f32 v143, v112, v113
	v_cvt_pk_bf16_f32 v144, v106, v107
	v_cvt_pk_bf16_f32 v145, v108, v109
	global_store_dwordx4 v147, v[142:145], s[60:61] nt
	v_add_u32_e32 v147, 0xc000, v146
	s_nop 0
	v_cvt_pk_bf16_f32 v142, v102, v103
	v_cvt_pk_bf16_f32 v143, v104, v105
	v_cvt_pk_bf16_f32 v144, v98, v99
	v_cvt_pk_bf16_f32 v145, v100, v101
	global_store_dwordx4 v147, v[142:145], s[60:61] nt
	v_add_u32_e32 v147, 0x20000, v146
	s_nop 0
	v_cvt_pk_bf16_f32 v142, v92, v93
	v_cvt_pk_bf16_f32 v143, v94, v95
	v_cvt_pk_bf16_f32 v144, v88, v89
	v_cvt_pk_bf16_f32 v145, v90, v91
	global_store_dwordx4 v147, v[142:145], s[60:61] nt
	v_add_u32_e32 v147, 0x24000, v146
	s_nop 0
	v_cvt_pk_bf16_f32 v142, v84, v85
	v_cvt_pk_bf16_f32 v143, v86, v87
	v_cvt_pk_bf16_f32 v144, v80, v81
	v_cvt_pk_bf16_f32 v145, v82, v83
	global_store_dwordx4 v147, v[142:145], s[60:61] nt
	v_add_u32_e32 v147, 0x28000, v146
	s_nop 0
	v_cvt_pk_bf16_f32 v142, v76, v77
	v_cvt_pk_bf16_f32 v143, v78, v79
	v_cvt_pk_bf16_f32 v144, v72, v73
	v_cvt_pk_bf16_f32 v145, v74, v75
	global_store_dwordx4 v147, v[142:145], s[60:61] nt
	v_add_u32_e32 v147, 0x2c000, v146
	s_nop 0
	v_cvt_pk_bf16_f32 v142, v12, v13
	v_cvt_pk_bf16_f32 v143, v14, v15
	v_cvt_pk_bf16_f32 v144, v8, v9
	v_cvt_pk_bf16_f32 v145, v10, v11
	global_store_dwordx4 v147, v[142:145], s[60:61] nt
	v_add_u32_e32 v147, 0x100, v146
	s_nop 0
	v_cvt_pk_bf16_f32 v142, v68, v69
	v_cvt_pk_bf16_f32 v143, v70, v71
	v_cvt_pk_bf16_f32 v144, v64, v65
	v_cvt_pk_bf16_f32 v145, v66, v67
	global_store_dwordx4 v147, v[142:145], s[60:61] nt
	v_add_u32_e32 v147, 0x4100, v146
	s_nop 0
	v_cvt_pk_bf16_f32 v142, v60, v61
	v_cvt_pk_bf16_f32 v143, v62, v63
	v_cvt_pk_bf16_f32 v144, v56, v57
	v_cvt_pk_bf16_f32 v145, v58, v59
	global_store_dwordx4 v147, v[142:145], s[60:61] nt
	v_add_u32_e32 v147, 0x8100, v146
	s_nop 0
	v_cvt_pk_bf16_f32 v142, v52, v53
	v_cvt_pk_bf16_f32 v143, v54, v55
	v_cvt_pk_bf16_f32 v144, v48, v49
	v_cvt_pk_bf16_f32 v145, v50, v51
	global_store_dwordx4 v147, v[142:145], s[60:61] nt
	v_add_u32_e32 v147, 0xc100, v146
	s_nop 0
	v_cvt_pk_bf16_f32 v142, v44, v45
	v_cvt_pk_bf16_f32 v143, v46, v47
	v_cvt_pk_bf16_f32 v144, v40, v41
	v_cvt_pk_bf16_f32 v145, v42, v43
	global_store_dwordx4 v147, v[142:145], s[60:61] nt
	v_add_u32_e32 v147, 0x20100, v146
	s_nop 0
	v_cvt_pk_bf16_f32 v142, v36, v37
	v_cvt_pk_bf16_f32 v143, v38, v39
	v_cvt_pk_bf16_f32 v144, v32, v33
	v_cvt_pk_bf16_f32 v145, v34, v35
	global_store_dwordx4 v147, v[142:145], s[60:61] nt
	v_add_u32_e32 v147, 0x24100, v146
	s_nop 0
	v_cvt_pk_bf16_f32 v142, v28, v29
	v_cvt_pk_bf16_f32 v143, v30, v31
	v_cvt_pk_bf16_f32 v144, v24, v25
	v_cvt_pk_bf16_f32 v145, v26, v27
	global_store_dwordx4 v147, v[142:145], s[60:61] nt
	v_add_u32_e32 v147, 0x28100, v146
	v_add_u32_e32 v146, 0x2c100, v146
	v_cvt_pk_bf16_f32 v142, v20, v21
	v_cvt_pk_bf16_f32 v143, v22, v23
	v_cvt_pk_bf16_f32 v144, v16, v17
	v_cvt_pk_bf16_f32 v145, v18, v19
	global_store_dwordx4 v147, v[142:145], s[60:61] nt
	s_nop 1
	v_cvt_pk_bf16_f32 v142, v4, v5
	v_cvt_pk_bf16_f32 v143, v6, v7
	v_cvt_pk_bf16_f32 v144, v0, v1
	v_cvt_pk_bf16_f32 v145, v2, v3
	global_store_dwordx4 v146, v[142:145], s[60:61] nt
	s_mov_b64 s[60:61], 0
; __device__ __forceinline__ unsigned cvt_pk_bf16(float lo, float hi) { f32x2_t v = {lo, hi}; bf16x2_t b = __builtin_convertvector(v, bf16x2_t); return __builtin_bit_cast(unsigned, b); }
; #define EPI_FENCE() asm volatile("" ::: "memory")
; #define EPI_LANE() int t__ = threadIdx.x; asm volatile("" : "+v"(t__)); const int wid__ = __builtin_amdgcn_readfirstlane(t__ >> 6); wr = wid__ >> 2; wc = wid__ & 3; fr = t__ & 15; fq = (t__ & 63) >> 4
;     template <int MODE> __device__ __forceinline__ void run(const f32x4 (&acc)[2][2][4][2], const Unit& u, int wr, int wc, int fr, int fq) const {
;         EPI_LANE();
;         const int pn = u.pn, colt = pn * BM, t = colt >> 9;
;         char* base = (MODE == 2) ? (char*)(O + (size_t)6 * ((size_t)MTOK * 512)) + ((size_t)(((pn - 12) * 128 + u.pm) * 8 + wid__)) * 16384
;                                  : (char*)(O + (size_t)t * ((size_t)MTOK * 512) + (size_t)u.pm * BM * 512 + (colt & 511));
;         unsigned off0 = (MODE == 2) ? (unsigned)((t__ & 63) * 16) : (unsigned)((wr * 64 + fr) * 512 + wc * 32 + 8 * fq) * 2u; asm volatile("" : "+v"(off0));
; #pragma unroll
;         for (int bj = 0; bj < 2; ++bj) {
; #pragma unroll
;             for (int ai = 0; ai < 2; ++ai)
; #pragma unroll
;                 for (int m = 0; m < 4; ++m) { const unsigned off = off0 + ((MODE == 2) ? (unsigned)(((ai * 4 + m) * 2 + bj) * 1024) : (unsigned)((ai * HALF + m * 16) * 512 + bj * HALF) * 2u);
;                     const f32x4 v0 = acc[ai][bj][m][0], v1 = acc[ai][bj][m][1];
;                     u32x4 w; w.x = cvt_pk_bf16(actf<MODE>(v0[0]), actf<MODE>(v0[1])); w.y = cvt_pk_bf16(actf<MODE>(v0[2]), actf<MODE>(v0[3]));
;                     w.z = cvt_pk_bf16(actf<MODE>(v1[0]), actf<MODE>(v1[1])); w.w = cvt_pk_bf16(actf<MODE>(v1[2]), actf<MODE>(v1[3]));
;                     *(u32x4*)(base + off) = w; }
;             EPI_FENCE();
;         }
;     }
.LBB0_413:
	s_andn2_b64 vcc, exec, s[60:61]
	s_cbranch_vccnz .LBB0_415
	s_ashr_i32 s55, s54, 31
	s_lshl_b64 s[60:61], s[54:55], 18
	s_add_u32 s55, s89, s60
	s_addc_u32 s61, s3, s61
	s_and_b32 s60, s62, 0x100
	v_mov_b32_e32 v142, v212
	s_lshl_b32 s60, s60, 1
	s_add_u32 s60, s55, s60
	v_readfirstlane_b32 s63, v142
	s_addc_u32 s61, s61, 0
	s_lshr_b32 s55, s63, 2
	s_and_b32 s55, s55, 0x3fffc0
	v_and_or_b32 v143, v142, 15, s55
	v_lshlrev_b32_e32 v143, 10, v143
	s_and_b32 s55, s63, 0xc0
	v_and_b32_e32 v142, 48, v142
	s_mov_b32 s24, 0x3e38aa3b
	v_or3_b32 v148, v143, s55, v142
	v_pk_mul_f32 v[142:143], v[126:127], s[24:25] op_sel_hi:[1,0]
	v_pk_mul_f32 v[144:145], v[128:129], s[24:25] op_sel_hi:[1,0]
	v_cvt_pk_bf16_f32 v142, v142, v143
	v_cvt_pk_bf16_f32 v143, v144, v145
	v_pk_mul_f32 v[144:145], v[122:123], s[24:25] op_sel_hi:[1,0]
	v_pk_mul_f32 v[146:147], v[124:125], s[24:25] op_sel_hi:[1,0]
	v_cvt_pk_bf16_f32 v144, v144, v145
	v_cvt_pk_bf16_f32 v145, v146, v147
	global_store_dwordx4 v148, v[142:145], s[60:61] nt
	v_pk_mul_f32 v[146:147], v[116:117], s[24:25] op_sel_hi:[1,0]
	v_add_u32_e32 v149, 0x4000, v148
	v_pk_mul_f32 v[142:143], v[118:119], s[24:25] op_sel_hi:[1,0]
	v_pk_mul_f32 v[144:145], v[120:121], s[24:25] op_sel_hi:[1,0]
	v_cvt_pk_bf16_f32 v142, v142, v143
	v_cvt_pk_bf16_f32 v143, v144, v145
	v_pk_mul_f32 v[144:145], v[114:115], s[24:25] op_sel_hi:[1,0]
	s_nop 0
	v_cvt_pk_bf16_f32 v144, v144, v145
	v_cvt_pk_bf16_f32 v145, v146, v147
	global_store_dwordx4 v149, v[142:145], s[60:61] nt
	v_pk_mul_f32 v[146:147], v[108:109], s[24:25] op_sel_hi:[1,0]
	v_add_u32_e32 v149, 0x8000, v148
	v_pk_mul_f32 v[142:143], v[110:111], s[24:25] op_sel_hi:[1,0]
	v_pk_mul_f32 v[144:145], v[112:113], s[24:25] op_sel_hi:[1,0]
	v_cvt_pk_bf16_f32 v142, v142, v143
	v_cvt_pk_bf16_f32 v143, v144, v145
	v_pk_mul_f32 v[144:145], v[106:107], s[24:25] op_sel_hi:[1,0]
	s_nop 0
	v_cvt_pk_bf16_f32 v144, v144, v145
	v_cvt_pk_bf16_f32 v145, v146, v147
	global_store_dwordx4 v149, v[142:145], s[60:61] nt
	v_pk_mul_f32 v[146:147], v[100:101], s[24:25] op_sel_hi:[1,0]
	v_add_u32_e32 v149, 0xc000, v148
	v_pk_mul_f32 v[142:143], v[102:103], s[24:25] op_sel_hi:[1,0]
	v_pk_mul_f32 v[144:145], v[104:105], s[24:25] op_sel_hi:[1,0]
	v_cvt_pk_bf16_f32 v142, v142, v143
	v_cvt_pk_bf16_f32 v143, v144, v145
	v_pk_mul_f32 v[144:145], v[98:99], s[24:25] op_sel_hi:[1,0]
	s_nop 0
	v_cvt_pk_bf16_f32 v144, v144, v145
	v_cvt_pk_bf16_f32 v145, v146, v147
	global_store_dwordx4 v149, v[142:145], s[60:61] nt
	v_pk_mul_f32 v[146:147], v[90:91], s[24:25] op_sel_hi:[1,0]
	v_add_u32_e32 v149, 0x20000, v148
	v_pk_mul_f32 v[142:143], v[92:93], s[24:25] op_sel_hi:[1,0]
	v_pk_mul_f32 v[144:145], v[94:95], s[24:25] op_sel_hi:[1,0]
	v_cvt_pk_bf16_f32 v142, v142, v143
	v_cvt_pk_bf16_f32 v143, v144, v145
	v_pk_mul_f32 v[144:145], v[88:89], s[24:25] op_sel_hi:[1,0]
	s_nop 0
	v_cvt_pk_bf16_f32 v144, v144, v145
	v_cvt_pk_bf16_f32 v145, v146, v147
	global_store_dwordx4 v149, v[142:145], s[60:61] nt
	v_pk_mul_f32 v[146:147], v[82:83], s[24:25] op_sel_hi:[1,0]
	v_add_u32_e32 v149, 0x24000, v148
	v_pk_mul_f32 v[142:143], v[84:85], s[24:25] op_sel_hi:[1,0]
	v_pk_mul_f32 v[144:145], v[86:87], s[24:25] op_sel_hi:[1,0]
	v_cvt_pk_bf16_f32 v142, v142, v143
	v_cvt_pk_bf16_f32 v143, v144, v145
	v_pk_mul_f32 v[144:145], v[80:81], s[24:25] op_sel_hi:[1,0]
	s_nop 0
	v_cvt_pk_bf16_f32 v144, v144, v145
	v_cvt_pk_bf16_f32 v145, v146, v147
	global_store_dwordx4 v149, v[142:145], s[60:61] nt
	v_pk_mul_f32 v[146:147], v[74:75], s[24:25] op_sel_hi:[1,0]
	v_add_u32_e32 v149, 0x28000, v148
	v_pk_mul_f32 v[142:143], v[76:77], s[24:25] op_sel_hi:[1,0]
	v_pk_mul_f32 v[144:145], v[78:79], s[24:25] op_sel_hi:[1,0]
	v_cvt_pk_bf16_f32 v142, v142, v143
	v_cvt_pk_bf16_f32 v143, v144, v145
	v_pk_mul_f32 v[144:145], v[72:73], s[24:25] op_sel_hi:[1,0]
	s_nop 0
	v_cvt_pk_bf16_f32 v144, v144, v145
	v_cvt_pk_bf16_f32 v145, v146, v147
	global_store_dwordx4 v149, v[142:145], s[60:61] nt
	v_pk_mul_f32 v[146:147], v[10:11], s[24:25] op_sel_hi:[1,0]
	v_add_u32_e32 v149, 0x2c000, v148
	v_pk_mul_f32 v[142:143], v[12:13], s[24:25] op_sel_hi:[1,0]
	v_pk_mul_f32 v[144:145], v[14:15], s[24:25] op_sel_hi:[1,0]
; __device__ __forceinline__ unsigned cvt_pk_bf16(float lo, float hi) { f32x2_t v = {lo, hi}; bf16x2_t b = __builtin_convertvector(v, bf16x2_t); return __builtin_bit_cast(unsigned, b); }
; #define EPI_FENCE() asm volatile("" ::: "memory")
; #define EPI_LANE() int t__ = threadIdx.x; asm volatile("" : "+v"(t__)); const int wid__ = __builtin_amdgcn_readfirstlane(t__ >> 6); wr = wid__ >> 2; wc = wid__ & 3; fr = t__ & 15; fq = (t__ & 63) >> 4
;     template <int MODE> __device__ __forceinline__ void run(const f32x4 (&acc)[2][2][4][2], const Unit& u, int wr, int wc, int fr, int fq) const {
;         EPI_LANE();
;         const int pn = u.pn, colt = pn * BM, t = colt >> 9;
;         char* base = (MODE == 2) ? (char*)(O + (size_t)6 * ((size_t)MTOK * 512)) + ((size_t)(((pn - 12) * 128 + u.pm) * 8 + wid__)) * 16384
;                                  : (char*)(O + (size_t)t * ((size_t)MTOK * 512) + (size_t)u.pm * BM * 512 + (colt & 511));
;         unsigned off0 = (MODE == 2) ? (unsigned)((t__ & 63) * 16) : (unsigned)((wr * 64 + fr) * 512 + wc * 32 + 8 * fq) * 2u; asm volatile("" : "+v"(off0));
; #pragma unroll
;         for (int bj = 0; bj < 2; ++bj) {
; #pragma unroll
;             for (int ai = 0; ai < 2; ++ai)
; #pragma unroll
;                 for (int m = 0; m < 4; ++m) { const unsigned off = off0 + ((MODE == 2) ? (unsigned)(((ai * 4 + m) * 2 + bj) * 1024) : (unsigned)((ai * HALF + m * 16) * 512 + bj * HALF) * 2u);
;                     const f32x4 v0 = acc[ai][bj][m][0], v1 = acc[ai][bj][m][1];
;                     u32x4 w; w.x = cvt_pk_bf16(actf<MODE>(v0[0]), actf<MODE>(v0[1])); w.y = cvt_pk_bf16(actf<MODE>(v0[2]), actf<MODE>(v0[3]));
;                     w.z = cvt_pk_bf16(actf<MODE>(v1[0]), actf<MODE>(v1[1])); w.w = cvt_pk_bf16(actf<MODE>(v1[2]), actf<MODE>(v1[3]));
;                     *(u32x4*)(base + off) = w; }
;             EPI_FENCE();
;         }
;     }
	v_cvt_pk_bf16_f32 v142, v142, v143
	v_cvt_pk_bf16_f32 v143, v144, v145
	v_pk_mul_f32 v[144:145], v[8:9], s[24:25] op_sel_hi:[1,0]
	s_nop 0
	v_cvt_pk_bf16_f32 v144, v144, v145
	v_cvt_pk_bf16_f32 v145, v146, v147
	global_store_dwordx4 v149, v[142:145], s[60:61] nt
	v_pk_mul_f32 v[146:147], v[66:67], s[24:25] op_sel_hi:[1,0]
	v_add_u32_e32 v149, 0x100, v148
	v_pk_mul_f32 v[142:143], v[68:69], s[24:25] op_sel_hi:[1,0]
	v_pk_mul_f32 v[144:145], v[70:71], s[24:25] op_sel_hi:[1,0]
	v_cvt_pk_bf16_f32 v142, v142, v143
	v_cvt_pk_bf16_f32 v143, v144, v145
	v_pk_mul_f32 v[144:145], v[64:65], s[24:25] op_sel_hi:[1,0]
	s_nop 0
	v_cvt_pk_bf16_f32 v144, v144, v145
	v_cvt_pk_bf16_f32 v145, v146, v147
	global_store_dwordx4 v149, v[142:145], s[60:61] nt
	v_pk_mul_f32 v[146:147], v[58:59], s[24:25] op_sel_hi:[1,0]
	v_add_u32_e32 v149, 0x4100, v148
	v_pk_mul_f32 v[142:143], v[60:61], s[24:25] op_sel_hi:[1,0]
	v_pk_mul_f32 v[144:145], v[62:63], s[24:25] op_sel_hi:[1,0]
	v_cvt_pk_bf16_f32 v142, v142, v143
	v_cvt_pk_bf16_f32 v143, v144, v145
	v_pk_mul_f32 v[144:145], v[56:57], s[24:25] op_sel_hi:[1,0]
	s_nop 0
	v_cvt_pk_bf16_f32 v144, v144, v145
	v_cvt_pk_bf16_f32 v145, v146, v147
	global_store_dwordx4 v149, v[142:145], s[60:61] nt
	v_pk_mul_f32 v[146:147], v[50:51], s[24:25] op_sel_hi:[1,0]
	v_add_u32_e32 v149, 0x8100, v148
	v_pk_mul_f32 v[142:143], v[52:53], s[24:25] op_sel_hi:[1,0]
	v_pk_mul_f32 v[144:145], v[54:55], s[24:25] op_sel_hi:[1,0]
	v_cvt_pk_bf16_f32 v142, v142, v143
	v_cvt_pk_bf16_f32 v143, v144, v145
	v_pk_mul_f32 v[144:145], v[48:49], s[24:25] op_sel_hi:[1,0]
	s_nop 0
	v_cvt_pk_bf16_f32 v144, v144, v145
	v_cvt_pk_bf16_f32 v145, v146, v147
	global_store_dwordx4 v149, v[142:145], s[60:61] nt
	v_pk_mul_f32 v[146:147], v[42:43], s[24:25] op_sel_hi:[1,0]
	v_add_u32_e32 v149, 0xc100, v148
	v_pk_mul_f32 v[142:143], v[44:45], s[24:25] op_sel_hi:[1,0]
	v_pk_mul_f32 v[144:145], v[46:47], s[24:25] op_sel_hi:[1,0]
	v_cvt_pk_bf16_f32 v142, v142, v143
	v_cvt_pk_bf16_f32 v143, v144, v145
	v_pk_mul_f32 v[144:145], v[40:41], s[24:25] op_sel_hi:[1,0]
	s_nop 0
	v_cvt_pk_bf16_f32 v144, v144, v145
	v_cvt_pk_bf16_f32 v145, v146, v147
	global_store_dwordx4 v149, v[142:145], s[60:61] nt
	v_pk_mul_f32 v[146:147], v[34:35], s[24:25] op_sel_hi:[1,0]
	v_add_u32_e32 v149, 0x20100, v148
	v_pk_mul_f32 v[142:143], v[36:37], s[24:25] op_sel_hi:[1,0]
	v_pk_mul_f32 v[144:145], v[38:39], s[24:25] op_sel_hi:[1,0]
	v_cvt_pk_bf16_f32 v142, v142, v143
	v_cvt_pk_bf16_f32 v143, v144, v145
	v_pk_mul_f32 v[144:145], v[32:33], s[24:25] op_sel_hi:[1,0]
	s_nop 0
	v_cvt_pk_bf16_f32 v144, v144, v145
	v_cvt_pk_bf16_f32 v145, v146, v147
	global_store_dwordx4 v149, v[142:145], s[60:61] nt
	v_pk_mul_f32 v[146:147], v[26:27], s[24:25] op_sel_hi:[1,0]
	v_add_u32_e32 v149, 0x24100, v148
	v_pk_mul_f32 v[142:143], v[28:29], s[24:25] op_sel_hi:[1,0]
	v_pk_mul_f32 v[144:145], v[30:31], s[24:25] op_sel_hi:[1,0]
	v_cvt_pk_bf16_f32 v142, v142, v143
	v_cvt_pk_bf16_f32 v143, v144, v145
	v_pk_mul_f32 v[144:145], v[24:25], s[24:25] op_sel_hi:[1,0]
	s_nop 0
	v_cvt_pk_bf16_f32 v144, v144, v145
	v_cvt_pk_bf16_f32 v145, v146, v147
	global_store_dwordx4 v149, v[142:145], s[60:61] nt
	v_pk_mul_f32 v[146:147], v[18:19], s[24:25] op_sel_hi:[1,0]
	v_add_u32_e32 v149, 0x28100, v148
	v_pk_mul_f32 v[142:143], v[20:21], s[24:25] op_sel_hi:[1,0]
	v_pk_mul_f32 v[144:145], v[22:23], s[24:25] op_sel_hi:[1,0]
	v_cvt_pk_bf16_f32 v142, v142, v143
	v_cvt_pk_bf16_f32 v143, v144, v145
	v_pk_mul_f32 v[144:145], v[16:17], s[24:25] op_sel_hi:[1,0]
	v_add_u32_e32 v148, 0x2c100, v148
	v_cvt_pk_bf16_f32 v144, v144, v145
	v_cvt_pk_bf16_f32 v145, v146, v147
	global_store_dwordx4 v149, v[142:145], s[60:61] nt
	v_pk_mul_f32 v[146:147], v[2:3], s[24:25] op_sel_hi:[1,0]
	s_nop 0
	v_pk_mul_f32 v[142:143], v[4:5], s[24:25] op_sel_hi:[1,0]
	v_pk_mul_f32 v[144:145], v[6:7], s[24:25] op_sel_hi:[1,0]
	v_cvt_pk_bf16_f32 v142, v142, v143
	v_cvt_pk_bf16_f32 v143, v144, v145
	v_pk_mul_f32 v[144:145], v[0:1], s[24:25] op_sel_hi:[1,0]
	s_nop 0
	v_cvt_pk_bf16_f32 v144, v144, v145
	v_cvt_pk_bf16_f32 v145, v146, v147
	global_store_dwordx4 v148, v[142:145], s[60:61] nt
